# deferred-seam WAIT: acquire (buffer_inv sc1) issued together with the first poll; failed first poll falls back to poll-then-acquire, on v20
# speedup vs baseline: 1.0035x; 1.0035x over previous
.LBB0_227:
	s_cmp_gt_i32 s79, 2
	s_cselect_b64 s[0:1], -1, 0
	s_and_b64 s[2:3], s[6:7], s[0:1]
	s_andn2_b64 vcc, exec, s[2:3]
	s_cbranch_vccnz .LBB0_277
	s_cmp_eq_u32 s100, 1
	s_cbranch_scc0 .Ldf1_orig
	s_cmp_eq_u32 s100, 1
	s_cbranch_scc0 .Ldf1_wd
	s_mov_b32 s100, 0
	v_cmp_eq_u32_e64 s[98:99], 0, v171
	s_nop 1
	s_and_saveexec_b64 s[98:99], s[98:99]
	s_cbranch_execz .Ldf1_wj
	v_mov_b32_e32 v247, 0x20004
	ds_read_b32 v248, v247
	v_readlane_b32 s96, v246, 1
	v_readlane_b32 s97, v246, 2
	v_mov_b32_e32 v249, 0x3a40
	s_mov_b32 s90, 0
	s_waitcnt lgkmcnt(0)
	v_readfirstlane_b32 s101, v248
	s_nop 3
	buffer_inv sc1
	global_load_dword v250, v249, s[96:97] sc1
	s_waitcnt vmcnt(0)
	v_readfirstlane_b32 s91, v250
	s_nop 0
	s_cmp_ge_u32 s91, s101
	s_cbranch_scc1 .Ldf1_wj

.LBB0_460:
	s_cmp_eq_u32 s100, 1
	s_cbranch_scc0 .Ldf3_wd
	s_mov_b32 s100, 0
	v_cmp_eq_u32_e64 s[98:99], 0, v171
	s_nop 1
	s_and_saveexec_b64 s[98:99], s[98:99]
	s_cbranch_execz .Ldf3_wj
	v_mov_b32_e32 v247, 0x20004
	ds_read_b32 v248, v247
	v_readlane_b32 s96, v246, 1
	v_readlane_b32 s97, v246, 2
	v_mov_b32_e32 v249, 0x3940
	s_mov_b32 s90, 0
	s_waitcnt lgkmcnt(0)
	v_readfirstlane_b32 s101, v248
	s_nop 3
	buffer_inv sc1
	global_load_dword v250, v249, s[96:97] sc1
	s_waitcnt vmcnt(0)
	v_readfirstlane_b32 s91, v250
	s_nop 0
	s_cmp_ge_u32 s91, s101
	s_cbranch_scc1 .Ldf3_wj

.Ldf4b_arr:
	s_or_b64 exec, exec, s[98:99]
	s_cmp_eq_u32 s32, 1
	s_cbranch_scc0 .Ldf4a_wd
	s_mov_b32 s32, 0
	v_cmp_eq_u32_e64 s[98:99], 0, v171
	s_nop 1
	s_and_saveexec_b64 s[98:99], s[98:99]
	s_cbranch_execz .Ldf4a_wj
	v_mov_b32_e32 v247, 0x20004
	ds_read_b32 v248, v247
	v_readlane_b32 s96, v246, 1
	v_readlane_b32 s97, v246, 2
	v_mov_b32_e32 v249, 0x3ac0
	s_mov_b32 s90, 0
	s_waitcnt lgkmcnt(0)
	v_readfirstlane_b32 s101, v248
	s_nop 3
	buffer_inv sc1
	global_load_dword v250, v249, s[96:97] sc1
	s_waitcnt vmcnt(0)
	v_readfirstlane_b32 s91, v250
	s_nop 0
	s_cmp_ge_u32 s91, s101
	s_cbranch_scc1 .Ldf4a_wj

.LBB0_523:
	s_cmp_lt_u32 s54, 0x400
	s_cbranch_scc1 .Ldf4b_wd
	s_cmp_eq_u32 s85, 1
	s_cbranch_scc0 .Ldf4b_wd
	s_mov_b32 s85, 0
	v_cmp_eq_u32_e64 s[98:99], 0, v171
	s_nop 1
	s_and_saveexec_b64 s[98:99], s[98:99]
	s_cbranch_execz .Ldf4b_wj
	v_mov_b32_e32 v247, 0x20004
	ds_read_b32 v248, v247
	v_readlane_b32 s96, v246, 1
	v_readlane_b32 s97, v246, 2
	v_mov_b32_e32 v249, 0x3b40
	s_mov_b32 s56, 0
	s_waitcnt lgkmcnt(0)
	v_readfirstlane_b32 s101, v248
	s_nop 3
	buffer_inv sc1
	global_load_dword v250, v249, s[96:97] sc1
	s_waitcnt vmcnt(0)
	v_readfirstlane_b32 s57, v250
	s_nop 0
	s_cmp_ge_u32 s57, s101
	s_cbranch_scc1 .Ldf4b_wj

.LBB0_649:
	s_cmp_eq_u32 s100, 1
	s_cbranch_scc0 .Ldf6_wd
	s_mov_b32 s100, 0
	v_cmp_eq_u32_e64 s[98:99], 0, v171
	s_nop 1
	s_and_saveexec_b64 s[98:99], s[98:99]
	s_cbranch_execz .Ldf6_wj
	v_mov_b32_e32 v247, 0x20004
	ds_read_b32 v248, v247
	v_readlane_b32 s96, v246, 1
	v_readlane_b32 s97, v246, 2
	v_mov_b32_e32 v249, 0x39c0
	s_mov_b32 s90, 0
	s_waitcnt lgkmcnt(0)
	v_readfirstlane_b32 s101, v248
	s_nop 3
	buffer_inv sc1
	global_load_dword v250, v249, s[96:97] sc1
	s_waitcnt vmcnt(0)
	v_readfirstlane_b32 s91, v250
	s_nop 0
	s_cmp_ge_u32 s91, s101
	s_cbranch_scc1 .Ldf6_wj
